# natten masked tiles: O accumulators kept in place (no per-tile copies), staging scratch moved off them, lazy rescale
# speedup vs baseline: 1.0072x; 1.0072x over previous
.LBB0_347:
	s_mov_b32 s99, 0
	s_bitcmp1_b32 s85, 0
	s_cselect_b32 s3, 0x2c00, 0
	s_cmp_gt_i32 s85, s97
	s_mov_b64 s[86:87], -1
	s_cbranch_scc1 .LBB0_435
	v_add_u32_e32 v2, s85, v195
	v_cmp_ge_u32_e32 vcc, v2, v194
	v_cmp_lt_u32_e64 s[86:87], v2, v214
	v_mov_b32_e32 v221, v163
	v_mov_b32_e32 v166, v0
	v_mov_b32_e32 v222, v220
	v_mov_b32_e32 v162, v219
	s_and_b64 vcc, vcc, s[86:87]
	s_and_saveexec_b64 s[86:87], vcc
	s_cbranch_execz .Lnat_inactive
	v_lshl_add_u32 v162, s3, 1, v215
	ds_read_b128 v[2:5], v162
	ds_read_b128 v[22:25], v162 offset:32
	ds_read_b128 v[54:57], v192 offset:47104
	ds_read_b128 v[58:61], v192 offset:47136
	s_waitcnt lgkmcnt(3)
	v_mfma_f32_32x32x16_bf16 v[38:53], v[2:5], v[130:133], 0
	s_waitcnt lgkmcnt(1)
	v_mfma_f32_32x32x16_bf16 v[6:21], v[2:5], v[54:57], 0
	ds_read_b128 v[2:5], v162 offset:64
	ds_read_b128 v[62:65], v192 offset:47168
	v_mfma_f32_32x32x16_bf16 v[38:53], v[22:25], v[134:137], v[38:53]
	s_waitcnt lgkmcnt(2)
	v_mfma_f32_32x32x16_bf16 v[6:21], v[22:25], v[58:61], v[6:21]
	s_waitcnt lgkmcnt(1)
	v_mfma_f32_32x32x16_bf16 v[38:53], v[2:5], v[138:141], v[38:53]
	s_waitcnt lgkmcnt(0)
	v_mfma_f32_32x32x16_bf16 v[6:21], v[2:5], v[62:65], v[6:21]
	ds_read_b128 v[2:5], v162 offset:96
	ds_read_b128 v[164:167], v192 offset:47200
	s_waitcnt lgkmcnt(1)
	v_mfma_f32_32x32x16_bf16 v[38:53], v[2:5], v[142:145], v[38:53]
	s_waitcnt lgkmcnt(0)
	v_mfma_f32_32x32x16_bf16 v[6:21], v[2:5], v[164:167], v[6:21]
	ds_read_b128 v[2:5], v162 offset:4608
	s_waitcnt lgkmcnt(0)
	v_mfma_f32_32x32x16_bf16 v[22:37], v[2:5], v[130:133], 0
	v_mfma_f32_32x32x16_bf16 v[2:17], v[2:5], v[54:57], 0
	ds_read_b128 v[54:57], v162 offset:4640
	s_waitcnt lgkmcnt(0)
	v_mfma_f32_32x32x16_bf16 v[22:37], v[54:57], v[134:137], v[22:37]
	v_mfma_f32_32x32x16_bf16 v[2:17], v[54:57], v[58:61], v[2:17]
	ds_read_b128 v[54:57], v162 offset:4672
	s_waitcnt lgkmcnt(0)
	v_mfma_f32_32x32x16_bf16 v[22:37], v[54:57], v[138:141], v[22:37]
	v_mfma_f32_32x32x16_bf16 v[2:17], v[54:57], v[62:65], v[2:17]
	ds_read_b128 v[54:57], v162 offset:4704
	s_waitcnt lgkmcnt(0)
	v_mfma_f32_32x32x16_bf16 v[22:37], v[54:57], v[142:145], v[22:37]
	v_mfma_f32_32x32x16_bf16 v[2:17], v[54:57], v[164:167], v[2:17]
	s_nop 10
	v_mov_b32_e32 v35, 0xff800000
	ds_read2_b32 v[26:27], v218 offset0:9 offset1:8
	ds_read2_b32 v[28:29], v218 offset0:11 offset1:10
	ds_read2_b32 v[30:31], v218 offset0:17 offset1:16
	ds_read2_b32 v[32:33], v218 offset0:19 offset1:18
	ds_read_b32 v34, v218 offset:172
	ds_read_b32 v162, v218 offset:100
	ds_read_b32 v164, v218 offset:96
	ds_read_b32 v166, v218 offset:132
	ds_read_b32 v177, v218 offset:104
	ds_read2_b32 v[178:179], v218 offset0:27 offset1:32
	ds_read_b32 v181, v218 offset:136
	ds_read2_b32 v[182:183], v218 offset0:35 offset1:40
	ds_read2_b32 v[184:185], v218 offset0:41 offset1:42
	s_waitcnt lgkmcnt(0)
	v_add_f32_e32 v27, v38, v27
	v_add_f32_e32 v26, v39, v26
	v_add_f32_e32 v29, v40, v29
	v_add_f32_e32 v28, v41, v28
	v_add_f32_e32 v31, v42, v31
	v_add_f32_e32 v30, v43, v30
	v_add_f32_e32 v33, v44, v33
	v_add_f32_e32 v32, v45, v32
	v_add_f32_e32 v164, v46, v164
	v_add_f32_e32 v162, v47, v162
	v_add_f32_e32 v177, v48, v177
	v_add_f32_e32 v178, v49, v178
	v_add_f32_e32 v179, v50, v179
	v_add_f32_e32 v166, v51, v166
	v_add_f32_e32 v181, v52, v181
	v_add_f32_e32 v182, v53, v182
	v_add_f32_e32 v183, v22, v183
	v_add_f32_e32 v184, v23, v184
	v_add_f32_e32 v185, v24, v185
	v_add_f32_e32 v23, v25, v34
	v_cndmask_b32_e64 v27, v35, v27, s[0:1]
	v_cndmask_b32_e64 v26, v35, v26, s[4:5]
	v_cndmask_b32_e64 v29, v35, v29, s[6:7]
	v_cndmask_b32_e64 v28, v35, v28, s[8:9]
	v_cndmask_b32_e64 v31, v35, v31, s[10:11]
	v_cndmask_b32_e64 v30, v35, v30, s[12:13]
	v_cndmask_b32_e64 v33, v35, v33, s[14:15]
	v_cndmask_b32_e64 v32, v35, v32, s[16:17]
	v_cndmask_b32_e64 v164, v35, v164, s[18:19]
	v_cndmask_b32_e64 v162, v35, v162, s[20:21]
	v_cndmask_b32_e64 v177, v35, v177, s[22:23]
	v_cndmask_b32_e64 v178, v35, v178, s[24:25]
	v_cndmask_b32_e64 v179, v35, v179, s[26:27]
	v_cndmask_b32_e64 v166, v35, v166, s[28:29]
	v_cndmask_b32_e64 v181, v35, v181, s[30:31]
	v_cndmask_b32_e64 v182, v35, v182, s[34:35]
	v_cndmask_b32_e64 v183, v35, v183, s[36:37]
	v_cndmask_b32_e64 v184, v35, v184, s[38:39]
	v_cndmask_b32_e64 v185, v35, v185, s[40:41]
	v_cndmask_b32_e64 v23, v35, v23, s[42:43]
	v_and_b32_e32 v24, 64, v200
	v_xor_b32_e32 v22, 32, v200
	v_add_u32_e32 v24, 64, v24
	v_cmp_lt_i32_e32 vcc, v22, v24
	s_nop 1
	v_cndmask_b32_e32 v22, v200, v22, vcc
	v_lshlrev_b32_e32 v22, 2, v22
	v_max3_f32 v24, v27, v26, v29
	v_max3_f32 v24, v24, v28, v31
	v_max3_f32 v24, v24, v30, v33
	v_max3_f32 v24, v24, v32, v164
	v_max3_f32 v24, v24, v162, v177
	v_max3_f32 v24, v24, v178, v179
	v_max3_f32 v24, v24, v166, v181
	v_max3_f32 v24, v24, v182, v183
	v_max3_f32 v24, v24, v184, v185
	s_mov_b32 s88, 0xff800000
	v_max3_f32 v24, v24, v23, s88
	ds_bpermute_b32 v25, v22, v24
	s_waitcnt lgkmcnt(0)
	v_max_f32_e32 v25, v25, v25
	v_max_f32_e32 v24, v24, v25
	v_add_f32_e32 v25, 0xc1000000, v24
	v_cmp_gt_f32_e32 vcc, v25, v163
	v_mov_b32_e32 v165, v220
	v_mov_b32_e32 v221, v163
	s_cbranch_vccz .LBB0_391
	v_max_f32_e32 v24, v24, v24
	v_max_f32_e32 v25, v163, v163
	v_max_f32_e32 v221, v25, v24
	v_sub_f32_e32 v24, v163, v221
	v_exp_f32_e32 v24, v24
	s_nop 0
	v_mul_f32_e32 v165, v220, v24
	v_pk_mul_f32 v[128:129], v[128:129], v[24:25] op_sel_hi:[1,0]
	v_pk_mul_f32 v[126:127], v[126:127], v[24:25] op_sel_hi:[1,0]
	v_pk_mul_f32 v[124:125], v[124:125], v[24:25] op_sel_hi:[1,0]
	v_pk_mul_f32 v[122:123], v[122:123], v[24:25] op_sel_hi:[1,0]
	v_pk_mul_f32 v[120:121], v[120:121], v[24:25] op_sel_hi:[1,0]
	v_pk_mul_f32 v[118:119], v[118:119], v[24:25] op_sel_hi:[1,0]
	v_pk_mul_f32 v[116:117], v[116:117], v[24:25] op_sel_hi:[1,0]
	v_pk_mul_f32 v[114:115], v[114:115], v[24:25] op_sel_hi:[1,0]
	v_pk_mul_f32 v[112:113], v[112:113], v[24:25] op_sel_hi:[1,0]
	v_pk_mul_f32 v[110:111], v[110:111], v[24:25] op_sel_hi:[1,0]
	v_pk_mul_f32 v[108:109], v[108:109], v[24:25] op_sel_hi:[1,0]
	v_pk_mul_f32 v[106:107], v[106:107], v[24:25] op_sel_hi:[1,0]
	v_pk_mul_f32 v[104:105], v[104:105], v[24:25] op_sel_hi:[1,0]
	v_pk_mul_f32 v[102:103], v[102:103], v[24:25] op_sel_hi:[1,0]
	v_pk_mul_f32 v[100:101], v[100:101], v[24:25] op_sel_hi:[1,0]
	v_pk_mul_f32 v[98:99], v[98:99], v[24:25] op_sel_hi:[1,0]
.LBB0_391:
	v_sub_f32_e32 v24, v27, v221
	v_exp_f32_e32 v167, v24
	v_sub_f32_e32 v24, v26, v221
	v_exp_f32_e32 v168, v24
	v_sub_f32_e32 v24, v29, v221
	v_exp_f32_e32 v169, v24
	v_sub_f32_e32 v24, v28, v221
	v_exp_f32_e32 v170, v24
	v_sub_f32_e32 v24, v31, v221
	v_exp_f32_e32 v171, v24
	v_sub_f32_e32 v24, v30, v221
	v_exp_f32_e32 v172, v24
	v_sub_f32_e32 v24, v33, v221
	v_exp_f32_e32 v173, v24
	v_sub_f32_e32 v24, v32, v221
	v_exp_f32_e32 v174, v24
	v_sub_f32_e32 v24, v164, v221
	v_exp_f32_e32 v175, v24
	v_sub_f32_e32 v24, v162, v221
	v_lshl_add_u32 v180, s3, 1, v216
	v_exp_f32_e32 v176, v24
	v_sub_f32_e32 v24, v177, v221
	v_exp_f32_e32 v177, v24
	v_sub_f32_e32 v24, v178, v221
	v_add_u32_e32 v162, 0x3000, v180
	v_exp_f32_e32 v178, v24
	ds_read2_b64 v[24:27], v162 offset0:128 offset1:130
	v_sub_f32_e32 v28, v179, v221
	v_exp_f32_e32 v179, v28
	v_cvt_pk_bf16_f32 v28, v167, v168
	v_cvt_pk_bf16_f32 v29, v169, v170
	v_cvt_pk_bf16_f32 v30, v171, v172
	v_cvt_pk_bf16_f32 v31, v173, v174
	v_add_u32_e32 v164, 0x4000, v180
	ds_read2_b64 v[186:189], v164 offset0:192 offset1:194
	s_waitcnt lgkmcnt(1)
	v_mfma_f32_32x32x16_bf16 v[114:129], v[24:27], v[28:31], v[114:129]
	v_sub_f32_e32 v24, v166, v221
	v_exp_f32_e32 v180, v24
	v_sub_f32_e32 v24, v181, v221
	v_exp_f32_e32 v181, v24
	v_sub_f32_e32 v24, v182, v221
	v_exp_f32_e32 v182, v24
	ds_read2_b64 v[24:27], v162 offset0:132 offset1:134
	s_waitcnt lgkmcnt(1)
	v_mfma_f32_32x32x16_bf16 v[98:113], v[186:189], v[28:31], v[98:113]
	v_sub_f32_e32 v28, v183, v221
	v_exp_f32_e32 v183, v28
	v_cvt_pk_bf16_f32 v28, v175, v176
	v_cvt_pk_bf16_f32 v29, v177, v178
	v_cvt_pk_bf16_f32 v30, v179, v180
	v_cvt_pk_bf16_f32 v31, v181, v182
	ds_read2_b64 v[222:225], v164 offset0:196 offset1:198
	v_sub_f32_e32 v23, v23, v221
	s_waitcnt lgkmcnt(1)
	v_mfma_f32_32x32x16_bf16 v[114:129], v[24:27], v[28:31], v[114:129]
	v_sub_f32_e32 v24, v184, v221
	v_exp_f32_e32 v184, v24
	v_sub_f32_e32 v24, v185, v221
	v_exp_f32_e32 v185, v24
	ds_read2_b64 v[24:27], v162 offset0:136 offset1:138
	v_exp_f32_e32 v186, v23
	v_sub_f32_e32 v23, 0xff800000, v221
	v_exp_f32_e32 v187, v23
	s_waitcnt lgkmcnt(1)
	v_mfma_f32_32x32x16_bf16 v[98:113], v[222:225], v[28:31], v[98:113]
	v_cvt_pk_bf16_f32 v28, v183, v184
	v_cvt_pk_bf16_f32 v29, v185, v186
	v_cvt_pk_bf16_f32 v30, v187, v187
	v_mov_b32_e32 v31, v30
	v_mov_b32_e32 v188, 0xff800000
	s_waitcnt lgkmcnt(0)
	v_mfma_f32_32x32x16_bf16 v[114:129], v[24:27], v[28:31], v[114:129]
	ds_read2_b64 v[24:27], v164 offset0:200 offset1:202
	s_waitcnt lgkmcnt(0)
	v_mfma_f32_32x32x16_bf16 v[98:113], v[24:27], v[28:31], v[98:113]
	v_mov_b32_e32 v23, 0xff800000
	ds_read2_b32 v[188:189], v218 offset0:1 offset1:0
	ds_read2_b32 v[208:209], v218 offset0:3 offset1:2
	ds_read_b32 v212, v218 offset:68
	ds_read_b32 v223, v218 offset:36
	ds_read2_b32 v[224:225], v218 offset0:19 offset1:8
	ds_read2_b32 v[226:227], v218 offset0:27 offset1:18
	ds_read2_b32 v[228:229], v218 offset0:33 offset1:25
	ds_read2_b32 v[230:231], v218 offset0:32 offset1:11
	ds_read2_b32 v[232:233], v218 offset0:35 offset1:10
	ds_read2_b32 v[234:235], v218 offset0:26 offset1:24
	ds_read2_b32 v[236:237], v218 offset0:34 offset1:16
	s_waitcnt lgkmcnt(0)
	v_add_f32_e32 v189, v18, v189
	v_add_f32_e32 v188, v19, v188
	v_add_f32_e32 v209, v20, v209
	v_add_f32_e32 v208, v21, v208
	v_add_f32_e32 v225, v2, v225
	v_add_f32_e32 v223, v3, v223
	v_add_f32_e32 v233, v4, v233
	v_add_f32_e32 v231, v5, v231
	v_add_f32_e32 v237, v6, v237
	v_add_f32_e32 v212, v7, v212
	v_add_f32_e32 v227, v8, v227
	v_add_f32_e32 v224, v9, v224
	v_add_f32_e32 v235, v10, v235
	v_add_f32_e32 v229, v11, v229
	v_add_f32_e32 v234, v12, v234
	v_add_f32_e32 v226, v13, v226
	v_add_f32_e32 v230, v14, v230
	v_add_f32_e32 v228, v15, v228
	v_add_f32_e32 v236, v16, v236
	v_add_f32_e32 v232, v17, v232
	v_cndmask_b32_e64 v189, v23, v189, s[44:45]
	v_cndmask_b32_e64 v188, v23, v188, s[46:47]
	v_cndmask_b32_e64 v209, v23, v209, s[48:49]
	v_cndmask_b32_e64 v208, v23, v208, s[50:51]
	v_cndmask_b32_e64 v225, v23, v225, s[52:53]
	v_cndmask_b32_e64 v223, v23, v223, s[54:55]
	v_cndmask_b32_e64 v233, v23, v233, s[56:57]
	v_cndmask_b32_e64 v231, v23, v231, s[58:59]
	v_cndmask_b32_e64 v237, v23, v237, s[60:61]
	v_cndmask_b32_e64 v212, v23, v212, s[62:63]
	v_cndmask_b32_e64 v227, v23, v227, s[64:65]
	v_cndmask_b32_e64 v224, v23, v224, s[66:67]
	v_cndmask_b32_e64 v235, v23, v235, s[68:69]
	v_cndmask_b32_e64 v229, v23, v229, s[70:71]
	v_cndmask_b32_e64 v234, v23, v234, s[72:73]
	v_cndmask_b32_e64 v226, v23, v226, s[74:75]
	v_cndmask_b32_e64 v230, v23, v230, s[76:77]
	v_cndmask_b32_e64 v228, v23, v228, s[78:79]
	v_cndmask_b32_e64 v236, v23, v236, s[80:81]
	v_cndmask_b32_e64 v232, v23, v232, s[82:83]
	v_max3_f32 v2, v189, s88, v188
	v_max3_f32 v2, v2, v209, v208
	v_max3_f32 v2, v2, v225, v223
	v_max3_f32 v2, v2, v233, v231
	v_max3_f32 v2, v2, v237, v212
	v_max3_f32 v2, v2, v227, v224
	v_max3_f32 v2, v2, v235, v229
	v_max3_f32 v2, v2, v234, v226
	v_max3_f32 v2, v2, v230, v228
	v_max3_f32 v2, v2, v236, v232
	ds_bpermute_b32 v3, v22, v2
	s_waitcnt lgkmcnt(0)
	v_max_f32_e32 v3, v3, v3
	v_max_f32_e32 v222, v2, v3
	v_add_f32_e32 v238, 0xc1000000, v222
	v_cmp_gt_f32_e32 vcc, v238, v0
	v_mov_b32_e32 v238, v219
	v_mov_b32_e32 v166, v0
	s_cbranch_vccz .LBB0_433
	v_max_f32_e32 v2, v222, v222
	v_max_f32_e32 v3, v0, v0
	v_max_f32_e32 v166, v3, v2
	v_sub_f32_e32 v2, v0, v166
	v_exp_f32_e32 v2, v2
	s_nop 0
	v_mul_f32_e32 v238, v219, v2
	v_pk_mul_f32 v[96:97], v[96:97], v[2:3] op_sel_hi:[1,0]
	v_pk_mul_f32 v[94:95], v[94:95], v[2:3] op_sel_hi:[1,0]
	v_pk_mul_f32 v[92:93], v[92:93], v[2:3] op_sel_hi:[1,0]
	v_pk_mul_f32 v[90:91], v[90:91], v[2:3] op_sel_hi:[1,0]
	v_pk_mul_f32 v[88:89], v[88:89], v[2:3] op_sel_hi:[1,0]
	v_pk_mul_f32 v[86:87], v[86:87], v[2:3] op_sel_hi:[1,0]
	v_pk_mul_f32 v[84:85], v[84:85], v[2:3] op_sel_hi:[1,0]
	v_pk_mul_f32 v[82:83], v[82:83], v[2:3] op_sel_hi:[1,0]
	v_pk_mul_f32 v[80:81], v[80:81], v[2:3] op_sel_hi:[1,0]
	v_pk_mul_f32 v[78:79], v[78:79], v[2:3] op_sel_hi:[1,0]
	v_pk_mul_f32 v[76:77], v[76:77], v[2:3] op_sel_hi:[1,0]
	v_pk_mul_f32 v[74:75], v[74:75], v[2:3] op_sel_hi:[1,0]
	v_pk_mul_f32 v[72:73], v[72:73], v[2:3] op_sel_hi:[1,0]
	v_pk_mul_f32 v[70:71], v[70:71], v[2:3] op_sel_hi:[1,0]
	v_pk_mul_f32 v[68:69], v[68:69], v[2:3] op_sel_hi:[1,0]
	v_pk_mul_f32 v[66:67], v[66:67], v[2:3] op_sel_hi:[1,0]
.LBB0_433:
	v_add_f32_e32 v167, 0, v167
	v_add_f32_e32 v167, v168, v167
	v_add_f32_e32 v167, v169, v167
	v_add_f32_e32 v167, v170, v167
	v_add_f32_e32 v167, v171, v167
	v_add_f32_e32 v167, v172, v167
	v_add_f32_e32 v167, v173, v167
	v_add_f32_e32 v167, v174, v167
	v_add_f32_e32 v167, v175, v167
	v_add_f32_e32 v167, v176, v167
	v_add_f32_e32 v167, v177, v167
	v_add_f32_e32 v167, v178, v167
	v_add_f32_e32 v167, v179, v167
	v_add_f32_e32 v167, v180, v167
	v_add_f32_e32 v167, v181, v167
	v_add_f32_e32 v167, v182, v167
	v_add_f32_e32 v167, v183, v167
	v_add_f32_e32 v167, v184, v167
	v_add_f32_e32 v167, v185, v167
	v_add_f32_e32 v167, v186, v167
	v_sub_f32_e32 v168, 0xff800000, v166
	v_exp_f32_e32 v172, v168
	v_sub_f32_e32 v168, v188, v166
	v_exp_f32_e32 v180, v168
	v_sub_f32_e32 v168, v209, v166
	v_exp_f32_e32 v181, v168
	v_sub_f32_e32 v168, v208, v166
	v_exp_f32_e32 v182, v168
	v_sub_f32_e32 v168, v225, v166
	v_add_f32_e32 v222, v165, v167
	v_add_f32_e32 v165, 0, v172
	v_exp_f32_e32 v183, v168
	v_sub_f32_e32 v168, v223, v166
	v_exp_f32_e32 v184, v168
	v_sub_f32_e32 v168, v233, v166
	v_exp_f32_e32 v185, v168
	v_sub_f32_e32 v168, v231, v166
	v_exp_f32_e32 v186, v168
	v_sub_f32_e32 v168, v237, v166
	v_exp_f32_e32 v187, v168
	ds_read2_b64 v[168:171], v162 offset0:128 offset1:130
	ds_read2_b64 v[176:179], v164 offset0:192 offset1:194
	v_sub_f32_e32 v173, v212, v166
	v_cvt_pk_bf16_f32 v172, v172, v172
	v_exp_f32_e32 v188, v173
	v_mov_b32_e32 v173, v172
	v_mov_b32_e32 v174, v172
	v_mov_b32_e32 v175, v172
	v_sub_f32_e32 v167, v189, v166
	v_exp_f32_e32 v167, v167
	s_waitcnt lgkmcnt(1)
	v_sub_f32_e32 v168, v227, v166
	v_exp_f32_e32 v189, v168
	v_sub_f32_e32 v168, v224, v166
	v_exp_f32_e32 v202, v168
	ds_read2_b64 v[168:171], v162 offset0:132 offset1:134
	v_add_f32_e32 v165, v167, v165
	v_add_f32_e32 v165, v180, v165
	s_waitcnt lgkmcnt(1)
	ds_read2_b64 v[176:179], v164 offset0:196 offset1:198
	v_sub_f32_e32 v173, v229, v166
	v_exp_f32_e32 v204, v173
	v_cvt_pk_bf16_f32 v174, v167, v180
	v_cvt_pk_bf16_f32 v175, v181, v182
	v_mov_b32_e32 v173, v172
	v_add_f32_e32 v165, v181, v165
	v_add_f32_e32 v165, v182, v165
	s_waitcnt lgkmcnt(1)
	v_mfma_f32_32x32x16_bf16 v[82:97], v[168:171], v[172:175], v[82:97]
	ds_read2_b64 v[168:171], v162 offset0:136 offset1:138
	v_add_f32_e32 v165, v183, v165
	v_add_f32_e32 v165, v184, v165
	v_add_f32_e32 v165, v185, v165
	v_add_f32_e32 v165, v186, v165
	v_sub_f32_e32 v203, v235, v166
	v_sub_f32_e32 v167, v234, v166
	s_waitcnt lgkmcnt(1)
	v_mfma_f32_32x32x16_bf16 v[66:81], v[176:179], v[172:175], v[66:81]
	ds_read2_b64 v[176:179], v164 offset0:200 offset1:202
	v_sub_f32_e32 v172, v226, v166
	v_exp_f32_e32 v180, v172
	v_cvt_pk_bf16_f32 v172, v183, v184
	v_cvt_pk_bf16_f32 v173, v185, v186
	v_cvt_pk_bf16_f32 v174, v187, v188
	v_cvt_pk_bf16_f32 v175, v189, v202
	v_add_f32_e32 v165, v187, v165
	v_exp_f32_e32 v203, v203
	s_waitcnt lgkmcnt(1)
	v_mfma_f32_32x32x16_bf16 v[82:97], v[168:171], v[172:175], v[82:97]
	v_sub_f32_e32 v168, v230, v166
	v_exp_f32_e32 v181, v168
	v_sub_f32_e32 v168, v228, v166
	v_exp_f32_e32 v182, v168
	v_sub_f32_e32 v168, v236, v166
	v_exp_f32_e32 v183, v168
	ds_read2_b64 v[168:171], v162 offset0:140 offset1:142
	s_waitcnt lgkmcnt(1)
	v_mfma_f32_32x32x16_bf16 v[66:81], v[176:179], v[172:175], v[66:81]
	ds_read2_b64 v[176:179], v164 offset0:204 offset1:206
	v_sub_f32_e32 v162, v232, v166
	v_exp_f32_e32 v167, v167
	v_exp_f32_e32 v162, v162
	v_add_f32_e32 v165, v188, v165
	v_add_f32_e32 v165, v189, v165
	v_add_f32_e32 v165, v202, v165
	v_add_f32_e32 v165, v203, v165
	v_cvt_pk_bf16_f32 v172, v203, v204
	v_cvt_pk_bf16_f32 v173, v167, v180
	v_cvt_pk_bf16_f32 v174, v181, v182
	v_cvt_pk_bf16_f32 v175, v183, v162
	v_add_f32_e32 v165, v204, v165
	v_add_f32_e32 v164, v167, v165
	s_waitcnt lgkmcnt(1)
	v_mfma_f32_32x32x16_bf16 v[82:97], v[168:171], v[172:175], v[82:97]
	v_add_f32_e32 v164, v180, v164
	v_add_f32_e32 v164, v181, v164
	v_add_f32_e32 v164, v182, v164
	v_add_f32_e32 v164, v183, v164
	v_add_f32_e32 v162, v162, v164
	v_add_f32_e32 v162, v238, v162
	s_waitcnt lgkmcnt(0)
	v_mfma_f32_32x32x16_bf16 v[66:81], v[176:179], v[172:175], v[66:81]
	s_mov_b32 s99, 1

.LBB0_442:
	s_add_i32 s3, s85, 1
	s_cmp_ge_i32 s3, s2
	s_cselect_b64 s[86:87], -1, 0
	s_and_b64 vcc, exec, s[86:87]
	s_cbranch_vccnz .LBB0_447
	v_mov_b32_e32 v168, v193
	s_bitcmp1_b32 s3, 0
	v_ashrrev_i32_e32 v0, 31, v168
	v_lshrrev_b32_e32 v0, 29, v0
	v_add_u32_e32 v0, v168, v0
	v_lshrrev_b32_e32 v169, 3, v0
	v_and_b32_e32 v0, 0xffffff8, v0
	s_cselect_b32 s88, 0x5800, 0
	v_sub_u32_e32 v0, v168, v0
	s_add_i32 s88, s88, 0
	v_mul_lo_u32 v169, v169, s91
	v_lshlrev_b32_e32 v0, 4, v0
	v_add3_u32 v0, s88, v169, v0
	v_add_u32_e32 v170, 0x100, v168
	s_waitcnt vmcnt(3)
	ds_write_b128 v0, v[146:149]
	v_ashrrev_i32_e32 v0, 31, v170
	v_lshrrev_b32_e32 v0, 29, v0
	v_add_u32_e32 v0, v170, v0
	v_lshrrev_b32_e32 v169, 3, v0
	v_and_b32_e32 v0, 0xffffff8, v0
	v_sub_u32_e32 v0, v170, v0
	v_mul_lo_u32 v169, v169, s91
	v_lshlrev_b32_e32 v0, 4, v0
	v_add3_u32 v0, s88, v169, v0
	s_waitcnt vmcnt(2)
	ds_write_b128 v0, v[150:153]
	v_lshlrev_b32_e32 v0, 4, v168
	v_and_b32_e32 v0, 0x70, v0
	v_add_u32_e32 v0, s88, v0
	v_lshrrev_b32_e32 v168, 3, v168
	v_mad_u64_u32 v[168:169], s[88:89], v168, s91, v[0:1]
	s_waitcnt vmcnt(1)
	ds_write_b128 v168, v[154:157] offset:13312
	v_lshrrev_b32_e32 v168, 3, v170
	s_add_i32 s85, s85, 2
	v_mad_u64_u32 v[168:169], s[88:89], v168, s91, v[0:1]
	s_cmp_ge_i32 s85, s2
	s_waitcnt vmcnt(0)
	ds_write_b128 v168, v[158:161] offset:13312
	s_cbranch_scc1 .LBB0_447
	s_cmp_gt_i32 s85, s97
	s_mov_b32 vcc_lo, s84
	s_cbranch_scc1 .LBB0_446
	s_add_i32 s85, s85, s96
	s_lshl_b32 vcc_lo, s85, 6
.LBB0_446:
	s_ashr_i32 vcc_hi, vcc_lo, 31
	s_lshl_b64 s[88:89], vcc, 7
	s_add_u32 s88, s92, s88
	s_addc_u32 s89, s93, s89
	s_lshl_b64 vcc, vcc, 1
	v_mov_b32_e32 v168, v193
	s_add_u32 vcc_lo, s94, vcc_lo
	s_addc_u32 vcc_hi, s95, vcc_hi
	v_ashrrev_i32_e32 v169, 31, v168
	v_add_u32_e32 v172, 0x100, v168
	v_lshlrev_b32_e32 v0, 4, v168
	v_lshl_add_u64 v[170:171], v[168:169], 4, s[88:89]
	v_ashrrev_i32_e32 v173, 31, v172
	v_and_b32_e32 v0, 0x70, v0
	v_lshl_add_u64 v[174:175], v[172:173], 4, s[88:89]
	global_load_dwordx4 v[146:149], v[170:171], off
	global_load_dwordx4 v[150:153], v[174:175], off
	v_lshl_add_u64 v[170:171], vcc, 0, v[0:1]
	v_ashrrev_i32_e32 v0, 3, v168
	s_movk_i32 s85, 0x1200
	v_mad_i64_i32 v[168:169], s[88:89], v0, s85, v[170:171]
	v_ashrrev_i32_e32 v0, 3, v172
	v_mad_i64_i32 v[170:171], s[88:89], v0, s85, v[170:171]
	global_load_dwordx4 v[154:157], v[168:169], off
	global_load_dwordx4 v[158:161], v[170:171], off
.LBB0_447:
	v_add_u32_e32 v218, 0x7c, v218
	s_andn2_b64 vcc, exec, s[86:87]
	s_add_i32 s84, s84, 64
	s_waitcnt lgkmcnt(0)
	s_barrier
	s_cbranch_vccz .LBB0_319
	s_cmp_eq_u32 s99, 1
	s_cbranch_scc1 .Lnat_skipcopy
	v_mov_b64_e32 v[80:81], v[16:17]
	v_mov_b64_e32 v[96:97], v[32:33]
	v_mov_b64_e32 v[112:113], v[48:49]
	v_mov_b64_e32 v[128:129], v[64:65]
	v_mov_b64_e32 v[78:79], v[14:15]
	v_mov_b64_e32 v[76:77], v[12:13]
	v_mov_b64_e32 v[74:75], v[10:11]
	v_mov_b64_e32 v[72:73], v[8:9]
	v_mov_b64_e32 v[70:71], v[6:7]
	v_mov_b64_e32 v[68:69], v[4:5]
	v_mov_b64_e32 v[66:67], v[2:3]
	v_mov_b64_e32 v[94:95], v[30:31]
	v_mov_b64_e32 v[92:93], v[28:29]
	v_mov_b64_e32 v[90:91], v[26:27]
	v_mov_b64_e32 v[88:89], v[24:25]
	v_mov_b64_e32 v[86:87], v[22:23]
	v_mov_b64_e32 v[84:85], v[20:21]
	v_mov_b64_e32 v[82:83], v[18:19]
	v_mov_b64_e32 v[110:111], v[46:47]
	v_mov_b64_e32 v[108:109], v[44:45]
	v_mov_b64_e32 v[106:107], v[42:43]
	v_mov_b64_e32 v[104:105], v[40:41]
	v_mov_b64_e32 v[102:103], v[38:39]
	v_mov_b64_e32 v[100:101], v[36:37]
	v_mov_b64_e32 v[98:99], v[34:35]
	v_mov_b64_e32 v[126:127], v[62:63]
	v_mov_b64_e32 v[124:125], v[60:61]
	v_mov_b64_e32 v[122:123], v[58:59]
	v_mov_b64_e32 v[120:121], v[56:57]
	v_mov_b64_e32 v[118:119], v[54:55]
	v_mov_b64_e32 v[116:117], v[52:53]
	v_mov_b64_e32 v[114:115], v[50:51]
.Lnat_skipcopy:
	v_mov_b32_e32 v219, v162
	v_mov_b32_e32 v220, v222
	s_mov_b32 s85, s3
	v_mov_b32_e32 v163, v221
	v_mov_b32_e32 v0, v166
	s_branch .LBB0_347
.Lnat_inactive:
	s_mov_b32 s99, 1
	s_branch .LBB0_434
